# v27 + FFN-down K-loop: x_in tile touched via LDS-DMA 8 iterations before the epilogue (L2/MALL prefetch)
# baseline (speedup 1.0000x reference)
; #define PG8_STAGE(bufoff, gbase, voff) do { _Pragma("unroll") for (int _i = 0; _i < 2; ++_i) \
;         __builtin_amdgcn_global_load_lds((const unsigned*)((const char*)(gbase) + (voff)[_i]), (LAS unsigned*)(lds + (bufoff) + ldsw + _i * 8192), 16, 0, PG8_AUX); } while (0)
; #define PG8_LDA(dst, b, h) do { _Pragma("unroll") for (int m = 0; m < 4; ++m) _Pragma("unroll") for (int k = 0; k < 2; ++k) dst[m][k] = *(const LAS bf16x8*)(lds + PG8_SA(b, h) + aoff + m * 2048 + k * 1024); } while (0)
; #define PG8_BAR __builtin_amdgcn_s_barrier()
; template <class Epi, class Sched>
; __device__ __forceinline__ void gemm_phase(LAS unsigned char* lds, const Gemm g, const Sched& S, const Epi& E) {
;     ...
;         for (int t = 0; t < nt; t += 2) {
;             const bool last = (t == nt - 2);
;             const char* a1 = cA + (size_t)(t + 1) * kstep;
;             const char* a2 = last ? nA : cA + (size_t)(t + 2) * kstep; const char* b2 = last ? nB : cB + (size_t)(t + 2) * kstep;
;             const char* a3 = a2 + kstep; const char* b3 = b2 + kstep;
;     ...
;             PG8_LDB(B0, 0, 0); PG8_LDB(B1, 0, 1); PG8_SCHED; PG8_LDA(At, 0, 0); PG8_STAGE(PG8_SA(1, 1), a1 + hstepA, voffA);
;             PG8_WAIT_V(8); PG8_WAIT_L(0); PG8_BAR; PG8_MMA(0, 0, At, B0); PG8_MMA(0, 1, At, B1); PG8_BAR; PG8_SCHED;
;             PG8_LDA(At, 0, 1); PG8_STAGE(PG8_SB(0, 0), b2, voffB); PG8_STAGE(PG8_SB(0, 1), b2 + hstepB, voffB); PG8_STAGE(PG8_SA(0, 0), a2, voffA);
;             PG8_WAIT_V(8); PG8_WAIT_L(0); PG8_BAR; PG8_MMA(1, 0, At, B0); PG8_MMA(1, 1, At, B1); PG8_BAR; PG8_SCHED;
;             PG8_LDB(B0, 1, 0); PG8_LDB(B1, 1, 1); PG8_SCHED; PG8_LDA(At, 1, 0); PG8_STAGE(PG8_SA(0, 1), a2 + hstepA, voffA);
;             PG8_WAIT_V(8); PG8_WAIT_L(0); PG8_BAR; PG8_MMA(0, 0, At, B0); PG8_MMA(0, 1, At, B1); PG8_BAR; PG8_SCHED;
;             PG8_LDA(At, 1, 1); PG8_STAGE(PG8_SB(1, 0), b3, voffB); PG8_STAGE(PG8_SB(1, 1), b3 + hstepB, voffB); PG8_STAGE(PG8_SA(1, 0), a3, voffA);
;             PG8_WAIT_V(8); PG8_WAIT_L(0); PG8_BAR; PG8_MMA(1, 0, At, B0); PG8_MMA(1, 1, At, B1); PG8_BAR; PG8_SCHED;
;     __device__ __forceinline__ void operator()(AccRef acc, const Unit& u, int wr, int wc, int fr, int fq) const {
;     ...
;                     const size_t off = (size_t)row * DM + col0 + bj * HALF;
;                     f32x4 x0 = *(const f32x4*)(xin + off), x1 = *(const f32x4*)(xin + off + 4);
.LBB0_679:
	s_cmp_eq_u32 s4, 70
	s_cbranch_scc0 .Lpfx2_skip
	v_lshrrev_b32_e32 v244, 3, v177
	v_and_b32_e32 v245, 7, v177
	v_lshrrev_b32_e32 v246, 6, v174
	v_lshl_add_u32 v244, v246, 5, v244
	v_readfirstlane_b32 s100, v246
	v_lshl_add_u32 v244, s61, 8, v244
	v_lshlrev_b32_e32 v244, 13, v244
	v_lshl_add_u32 v244, v245, 7, v244
	s_nop 3
	s_lshl_b32 s100, s100, 10
	s_add_i32 m0, s100, 0x20000
	s_lshl_b32 s100, s60, 10
	v_add_u32_e32 v244, s100, v244
	global_load_lds_dwordx4 v244, s[44:45]
	v_add_u32_e32 v245, 0x10000, v244
	global_load_lds_dwordx4 v245, s[44:45]
	v_add_u32_e32 v246, 0x20000, v244
	global_load_lds_dwordx4 v246, s[44:45]
	v_add_u32_e32 v247, 0x30000, v244
	global_load_lds_dwordx4 v247, s[44:45]
